# v16 + P1: short-conv items on waves 4-7 concurrent with retention-image items on waves 0-4 (barrier between removed, disjoint LDS)
# baseline (speedup 1.0000x reference)
; #define LAS __attribute__((address_space(3)))
; #define GAS __attribute__((address_space(1)))
; __device__ __forceinline__ void prep_phase(Frame& F, CArgs a, int l, unsigned long long& tm_acc) {
;     ...
;     {
;         const GAS float* cw = ((const GAS float*)a->in[I_CONVW]) + (size_t)l * 3 * 1536; const GAS float* cb = ((const GAS float*)a->in[I_CONVB]) + (size_t)l * 1536;
;         LAS unsigned char* T = F.lds + F.wave * 9216;
;         const int lane = F.lane, c8 = (lane & 7) * 8, rb = lane >> 3, gl = lane & 15, gg = lane >> 4;
;         const int gw = F.wave * F.G + F.blk, NGW = F.G * 8;
;         for (int wi = gw; wi < 144 * 8; wi += NGW) {
;             const int tile = wi >> 3, c0 = (wi & 7) * 64, row0 = tile * 64;
;             if (l == DEPTH - 1 && row0 < MC) continue;
;             int t0, L; GAS bf16_t *ud, *xd;
;             if (row0 < MC) { const int sq = row0 >> 8; t0 = row0 & 255; L = CTXL; ud = (GAS bf16_t*)(ws + WS_UTBC) + (size_t)sq * 512 * CTXL; xd = (GAS bf16_t*)(ws + WS_X0TC) + (size_t)sq * 512 * CTXL; }
;             else { const int r = row0 - MC, sq = r >> 11; t0 = r & 2047; L = SEQ; ud = (GAS bf16_t*)(ws + WS_UTBL) + (size_t)sq * 512 * SEQ; xd = (GAS bf16_t*)(ws + WS_X0TL) + (size_t)sq * 512 * SEQ; }
; #pragma unroll 1
;             for (int ps = 0; ps < 2; ++ps) {
;                 const int rbase = row0 + ps * 32 + rb * 4, tbase = t0 + ps * 32 + rb * 4;
.LBB0_626:
	s_mul_i32 s5, s4, s3
	s_add_i32 s48, s5, s2
	s_movk_i32 s100, 0x7fff
	s_movk_i32 s101, 0x7fff
	s_cmp_lt_u32 s4, 5
	s_cbranch_scc1 .Lpb_w4
	s_sub_i32 s100, s4, 5
	s_lshl_b32 s100, s100, 8
	s_add_i32 s100, s100, s2
	s_cmp_gt_u32 s4, 6
	s_cbranch_scc1 .Lpb_done
	s_cmp_gt_u32 s2, 0x7f
	s_cbranch_scc1 .Lpb_done
	s_sub_i32 s101, s4, 5
	s_lshl_b32 s101, s101, 7
	s_add_i32 s101, s101, s2
	s_addk_i32 s101, 0x380
	s_branch .Lpb_done
.Lpb_w4:
	s_cmp_lg_u32 s4, 4
	s_cbranch_scc1 .Lpb_done
	s_cmp_lt_u32 s2, 0x80
	s_cbranch_scc1 .Lpb_done
	s_add_i32 s100, s2, 0x280
.Lpb_done:
	v_and_b32_e32 v120, 7, v0
	v_and_b32_e32 v124, 15, v0
	s_cmpk_lt_i32 s48, 0x480
	s_waitcnt vmcnt(0)
	v_lshlrev_b32_e32 v2, 3, v118
	v_lshlrev_b32_e32 v1, 3, v120
	s_cselect_b64 s[8:9], -1, 0
	s_cmpk_gt_i32 s100, 0x47f
	v_lshrrev_b32_e32 v119, 2, v124
	v_or_b32_e32 v126, 16, v124
	v_or_b32_e32 v125, 32, v124
	v_or_b32_e32 v122, 48, v124
	v_and_b32_e32 v123, 24, v2
	s_barrier
	s_cbranch_scc1 .LBB0_660
	s_load_dwordx4 s[24:27], s[0:1], 0x40
	v_readlane_b32 s10, v255, 42
	s_mov_b32 s18, s10
	s_mul_hi_u32 s5, s10, 0x4800
	s_mulk_i32 s10, 0x4800
	v_readlane_b32 s11, v255, 43
	s_waitcnt lgkmcnt(0)
	s_add_u32 s10, s24, s10
	s_mul_i32 s12, s18, 0x1800
	s_addc_u32 s11, s25, s5
	s_mul_hi_u32 s13, s18, 0x1800
	s_add_u32 s12, s26, s12
	s_addc_u32 s13, s27, s13
	s_cmp_eq_u32 s18, 3
	s_mul_i32 s5, s4, 0x2400
	s_cselect_b64 s[18:19], -1, 0
	s_add_i32 s24, s5, 0
	s_add_u32 s5, s6, 0x3a200000
	s_addc_u32 s49, s7, 0
	s_add_u32 s50, s6, 0x3ab00000
	s_addc_u32 s51, s7, 0
	v_lshrrev_b32_e32 v2, 1, v118
	s_add_u32 s52, s6, 0x3aa00000
	v_and_b32_e32 v127, 24, v2
	s_addc_u32 s53, s7, 0
	v_and_b32_e32 v121, 28, v2
	v_mov_b32_e32 v3, s24
	v_lshl_add_u32 v4, v120, 4, s24
	v_or_b32_e32 v5, v127, v119
	s_movk_i32 s24, 0x90
	v_or_b32_e32 v2, 3, v2
	s_add_u32 s54, s6, 0x3b300000
	v_mad_u32_u24 v3, v5, s24, v3
	v_mul_u32_u24_e32 v5, 0x90, v121
	v_mul_u32_u24_e32 v2, 0x90, v2
	s_addc_u32 s55, s7, 0
	v_add_u32_e32 v128, v3, v123
	v_add_u32_e32 v129, v4, v5
	v_add_u32_e32 v130, v4, v2
	s_mov_b32 s60, s100
	s_branch .LBB0_629
.LBB0_628:
	s_mov_b32 s60, s101
	s_movk_i32 s101, 0x7fff
	s_cmpk_gt_i32 s60, 0x47f
	s_cbranch_scc1 .LBB0_660

; #define TM_BEGIN(k) do { if ((TIMEMASK >> (k)) & 1u) tm_t0 = __builtin_amdgcn_s_memrealtime(); } while (0)
; #define TM_END(k) do { if ((TIMEMASK >> (k)) & 1u) tm_acc += __builtin_amdgcn_s_memrealtime() - tm_t0; } while (0)
; #define LAS __attribute__((address_space(3)))
; #define GAS __attribute__((address_space(1)))
; __device__ __forceinline__ float ret_lg2(const GAS float* rdec, int l, int dirh) { const float p = rdec[l * 8 + dirh]; return log1pf(-expf(p)) * 1.4426950408889634f; }
; __device__ __forceinline__ void prep_phase(Frame& F, CArgs a, int l, unsigned long long& tm_acc) {
;     ...
;     __syncthreads();
;     TM_END(17); TM_BEGIN(18);
;     {
;         GAS bf16_t* AB = (GAS bf16_t*)(ws + WS_ABUF); GAS bf16_t* BB = (GAS bf16_t*)(ws + WS_BBUF); GAS bf16_t* KT = (GAS bf16_t*)(ws + WS_KT);
;         GAS bf16_t* QRp = (GAS bf16_t*)(ws + WS_QR); GAS bf16_t* KRp = (GAS bf16_t*)(ws + WS_KRB);
;         const GAS float* rope = (const GAS float*)(ws + WS_ROPE);
;         LAS unsigned char* T = F.lds + F.wave * 8704;
;         const int lane = F.lane, ts = lane >> 3, c = lane & 7, gl = lane & 15, gg = lane >> 4;
;         const int gw = F.wave * F.G + F.blk, NGW = F.G * 8;
;         for (int wi = gw; wi < NU * 8; wi += NGW) {
;             const int u = wi >> 3, tb = (wi >> 1) & 3, half = wi & 1, bh = u / 9, ci = u % 9, b = bh >> 2, h = bh & 3;
;             const int row0 = chunk_row0(b, ci); const bool isctx = ci == 0;
;             const float lf = ret_lg2((const GAS float*)a->in[I_RDEC], l, h), lb = ret_lg2((const GAS float*)a->in[I_RDEC], l, 4 + h);
;             const int dA = half * 128 + 8 * c, dB = dA + 64;
; #pragma unroll 1
.LBB0_660:
	s_andn2_b64 vcc, exec, s[8:9]
	s_cbranch_vccnz .LBB0_677
	s_add_u32 s12, s6, 0x3d000000
	s_addc_u32 s13, s7, 0
	s_add_u32 s18, s6, 0x53800000
	s_addc_u32 s19, s7, 0
	v_readlane_b32 s8, v255, 42
	s_add_u32 s26, s6, 0x54a00000
	v_readlane_b32 s9, v255, 43
	v_lshlrev_b32_e32 v202, 2, v1
	s_addc_u32 s27, s7, 0
	s_lshl_b32 s34, s8, 3
	v_lshl_add_u64 v[2:3], s[6:7], 0, v[202:203]
	s_mov_b64 s[8:9], 0x200000
	s_waitcnt vmcnt(11)
	v_lshl_add_u64 v[58:59], v[2:3], 0, s[8:9]
	v_lshrrev_b32_e32 v2, 1, v0
	s_mulk_i32 s4, 0x2200
	v_and_b32_e32 v6, 24, v2
	s_add_i32 s4, s4, 0x12000
	v_lshlrev_b32_e32 v202, 1, v6
	s_load_dwordx2 s[40:41], s[0:1], 0xb8
	v_mov_b32_e32 v4, s4
	v_lshl_add_u32 v5, v120, 4, s4
	v_lshl_add_u64 v[2:3], s[6:7], 0, v[202:203]
	s_mov_b64 s[4:5], 0x43c00000
	v_lshl_add_u64 v[60:61], v[2:3], 0, s[4:5]
	s_mov_b64 s[4:5], 0x40600000
	v_lshrrev_b32_e32 v118, 3, v118
	v_lshl_add_u64 v[62:63], v[2:3], 0, s[4:5]
	v_or_b32_e32 v2, v6, v119
	s_movk_i32 s4, 0x110
	v_or_b32_e32 v9, 64, v124
	v_or_b32_e32 v11, 0x50, v124
	v_or_b32_e32 v13, 0x60, v124
	v_or_b32_e32 v15, 0x70, v124
	v_mad_u32_u24 v3, v2, s4, v4
	v_mul_u32_u24_e32 v7, 0x110, v118
	v_lshlrev_b32_e32 v2, 8, v124
	v_lshlrev_b32_e32 v4, 8, v126
	v_lshlrev_b32_e32 v6, 8, v125
	v_lshlrev_b32_e32 v8, 8, v122
	v_lshlrev_b32_e32 v10, 8, v9
	v_lshlrev_b32_e32 v12, 8, v11
	v_lshlrev_b32_e32 v14, 8, v13
	v_lshlrev_b32_e32 v16, 8, v15
	v_or_b32_e32 v119, 8, v118
	v_or_b32_e32 v120, 16, v118
	v_or_b32_e32 v121, 24, v118
	v_mul_hi_u32_u24_e32 v65, 0x600, v124
	v_mul_u32_u24_e32 v64, 0x600, v124
	v_mul_hi_u32_u24_e32 v67, 0x600, v126
	v_mul_u32_u24_e32 v66, 0x600, v126
	v_mul_hi_u32_u24_e32 v69, 0x600, v125
	v_mul_u32_u24_e32 v68, 0x600, v125
	s_waitcnt vmcnt(10)
	v_mul_hi_u32_u24_e32 v71, 0x600, v122
	v_mul_u32_u24_e32 v70, 0x600, v122
	v_mul_hi_u32_u24_e32 v73, 0x600, v9
	v_mul_u32_u24_e32 v72, 0x600, v9
	v_mul_hi_u32_u24_e32 v75, 0x600, v11
	v_mul_u32_u24_e32 v74, 0x600, v11
	v_mul_hi_u32_u24_e32 v77, 0x600, v13
	v_mul_u32_u24_e32 v76, 0x600, v13
	v_mul_hi_u32_u24_e32 v79, 0x600, v15
	v_mul_u32_u24_e32 v78, 0x600, v15
	v_add_u32_e32 v122, v5, v7
	v_add_u32_e32 v123, v3, v123
	v_lshlrev_b32_e32 v80, 1, v2
	v_lshlrev_b32_e32 v82, 1, v4
	v_lshlrev_b32_e32 v84, 1, v6
	v_lshlrev_b32_e32 v86, 1, v8
	v_lshlrev_b32_e32 v88, 1, v10
	s_waitcnt vmcnt(9)
	v_lshlrev_b32_e32 v90, 1, v12
	v_lshlrev_b32_e32 v92, 1, v14
	s_waitcnt vmcnt(8)
	v_lshlrev_b32_e32 v94, 1, v16
	s_branch .LBB0_663
